# scan LDS-DMA loads use scalar base + 32-bit lane offset addressing instead of 64-bit per-lane addresses
# baseline (speedup 1.0000x reference)
; #define SP_BAR() asm volatile("s_waitcnt lgkmcnt(0)\n\ts_barrier" ::: "memory")
; #define SP_WAIT() asm volatile("s_waitcnt vmcnt(36)" ::: "memory")
; __device__ __forceinline__ void p3_rwkv_state(Frame& F, const Args& a) {
;     constexpr int NC = T / 16;
;     const int xcd_ = blockIdx.x & 7, sl_ = blockIdx.x >> 3, head = 2 * xcd_ + (sl_ >> 2), ib = sl_ & 3, lane = F.lane, rg = lane >> 4;
;     const unsigned lds0 = (unsigned)(uintptr_t)F.lds;
;     const bool loader = F.wave >= 1 && F.wave <= 3; const int lw = F.wave - 1;
;     ...
;     if (loader) {
;         DmaPtrs P; rw_dma_init(a, P, head, ib, lw, lane);
;         for (int n = 0; n < SP_D; ++n) rw_dma_issue(P, lw, lane, lds0 + (unsigned)(n % SP_R) * SP_SLOT);
;         SP_WAIT();
;         SP_BAR();
.LBB0_399:
	s_or_b64 exec, exec, s[0:1]
	s_waitcnt lgkmcnt(0)
	s_barrier
	v_mbcnt_lo_u32_b32 v76, -1, 0
	v_mbcnt_hi_u32_b32 v76, -1, v76
	s_cmp_lt_i32 s94, 64
	s_cbranch_scc0 .Lrw_late_entry
	s_lshl_b32 s0, s94, 1
	s_and_b32 s0, s0, 14
	s_lshr_b32 s1, s94, 5
	s_add_i32 s0, s0, s1
	s_bfe_u32 s4, s94, 0x20003
	s_mov_b32 s19, m0
	s_cmp_eq_u32 s92, 0
	s_cbranch_scc1 .Lscan_consumer
	s_cmp_eq_u32 s92, 6
	s_cbranch_scc1 .Lscan_ldsmall
	s_cmp_eq_u32 s92, 4
	s_cbranch_scc1 .Lscan_idle
	s_cmp_eq_u32 s92, 7
	s_cbranch_scc1 .Lscan_idle
	s_add_i32 s3, s92, -1
	s_min_u32 s3, s3, 3
	s_lshl_b32 s2, s0, 11
	s_lshl_b32 s5, s3, 25
	s_add_u32 s2, s2, s5
	s_add_u32 s12, s88, s2
	s_addc_u32 s13, s89, 0
	v_lshlrev_b32_e32 v0, 4, v76
	s_lshl_b32 s14, s3, 11
	s_mov_b32 s15, 0
	s_mov_b32 s18, 0
.Lscan_ldbig_pro:
	s_add_i32 s16, s15, s14
	s_mov_b32 m0, s16
	s_add_i32 s15, s15, 0x2800
	global_load_lds_dwordx4 v0, s[12:13]
	global_load_lds_dwordx4 v0, s[12:13] offset:1024
	s_cmp_eq_u32 s15, 0x25800
	s_cselect_b32 s15, 0, s15
	s_add_u32 s12, s12, 0x8000
	s_addc_u32 s13, s13, 0
	s_add_i32 s18, s18, 1
	s_cmp_lt_u32 s18, 12
	s_cbranch_scc1 .Lscan_ldbig_pro
	s_waitcnt vmcnt(18)
	s_barrier
	s_mov_b32 s18, 0
	s_movk_i32 s17, 0x100

; #define SP_BAR() asm volatile("s_waitcnt lgkmcnt(0)\n\ts_barrier" ::: "memory")
; #define SP_WAIT() asm volatile("s_waitcnt vmcnt(36)" ::: "memory")
; __device__ __forceinline__ void p3_rwkv_state(Frame& F, const Args& a) {
;     ...
;         for (int n = 0; n < NC; n += 2) {
;             if (n + SP_D + 1 < NC) { rw_dma_issue(P, lw, lane, lds0 + (unsigned)((n + SP_D) % SP_R) * SP_SLOT); rw_dma_issue(P, lw, lane, lds0 + (unsigned)((n + SP_D + 1) % SP_R) * SP_SLOT); SP_WAIT(); }
;             else asm volatile("s_waitcnt vmcnt(0)" ::: "memory");
;             SP_BAR();
.Lscan_ldbig_go:
	s_add_i32 s16, s15, s14
	s_mov_b32 m0, s16
	s_add_i32 s15, s15, 0x2800
	global_load_lds_dwordx4 v0, s[12:13]
	global_load_lds_dwordx4 v0, s[12:13] offset:1024
	s_cmp_eq_u32 s15, 0x25800
	s_cselect_b32 s15, 0, s15
	s_add_u32 s12, s12, 0x8000
	s_addc_u32 s13, s13, 0
	s_add_i32 s16, s15, s14
	s_mov_b32 m0, s16
	s_add_i32 s15, s15, 0x2800
	global_load_lds_dwordx4 v0, s[12:13]
	global_load_lds_dwordx4 v0, s[12:13] offset:1024
	s_cmp_eq_u32 s15, 0x25800
	s_cselect_b32 s15, 0, s15
	s_add_u32 s12, s12, 0x8000
	s_addc_u32 s13, s13, 0
	s_waitcnt vmcnt(18)
	s_branch .Lscan_ldbig_bar

; #define SP_BAR() asm volatile("s_waitcnt lgkmcnt(0)\n\ts_barrier" ::: "memory")
; #define SP_WAIT() asm volatile("s_waitcnt vmcnt(36)" ::: "memory")
; __device__ __forceinline__ void rw_dma_init(const Args& a, DmaPtrs& P, int head, int ib, int lw, int lane) {
;     const unsigned char* outb = (const unsigned char*)a.out; const unsigned char* ws = a.ws; const size_t c0 = (size_t)head * 2048;
;     if (lw == 0) { P.p[0] = outb + OUT_W1A + c0 + lane * 16; P.p[1] = P.p[0] + 1024; P.p[2] = outb + OUT_QA + c0 + lane * 16; P.p[3] = P.p[2] + 1024; P.off[0] = 0u; P.off[1] = 1024u; P.off[2] = 2048u; P.off[3] = 3072u; }
;     else if (lw == 1) { P.p[0] = outb + OUT_BT + c0 + lane * 16; P.p[1] = P.p[0] + 1024; P.p[2] = outb + OUT_KT + c0 + lane * 16; P.p[3] = P.p[2] + 1024; P.off[0] = 4096u; P.off[1] = 5120u; P.off[2] = 6144u; P.off[3] = 7168u; }
;     else { const int l32 = lane & 31; P.p[0] = ws + WS_U0 + c0 + ib * 512 + l32 * 16; P.p[1] = ws + WS_Y0 + c0 + ib * 512 + l32 * 16; P.p[2] = ws + WS_VS + c0 + ib * 512 + l32 * 16; P.p[3] = ws + WS_DD + (size_t)head * 256 + (lane & 15) * 16;
;            P.off[0] = 8192u; P.off[1] = 8704u; P.off[2] = 9216u; P.off[3] = 9728u; }
; }
; __device__ __forceinline__ void rw_dma_issue(DmaPtrs& P, int lw, int lane, unsigned slot_lds) {
;     if (lw < 2) {
; #pragma unroll
;         for (int q = 0; q < 4; ++q) attn_body::glds16(P.p[q], (unsigned)__builtin_amdgcn_readfirstlane(slot_lds + P.off[q]));
;     } else {
;         if (lane < 32) {
; #pragma unroll
;             for (int q = 0; q < 3; ++q) attn_body::glds16(P.p[q], (unsigned)__builtin_amdgcn_readfirstlane(slot_lds + P.off[q])); }
;         if (lane < 16) attn_body::glds16(P.p[3], (unsigned)__builtin_amdgcn_readfirstlane(slot_lds + P.off[3]));
;     }
; #pragma unroll
;     for (int q = 0; q < 4; ++q) P.p[q] += (lw == 2 && q == 3) ? 16 * 256 : 16 * 2048;
; }
; __device__ __forceinline__ void p3_rwkv_state(Frame& F, const Args& a) {
;     ...
;     if (loader) {
;         DmaPtrs P; rw_dma_init(a, P, head, ib, lw, lane);
;         for (int n = 0; n < SP_D; ++n) rw_dma_issue(P, lw, lane, lds0 + (unsigned)(n % SP_R) * SP_SLOT);
;         SP_WAIT();
;         SP_BAR();
.Lscan_ldsmall:
	s_lshl_b32 s2, s0, 11
	s_lshl_b32 s5, s4, 9
	s_add_u32 s2, s2, s5
	v_and_b32_e32 v0, 31, v76
	v_lshlrev_b32_e32 v0, 4, v0
	v_add_u32_e32 v0, s2, v0
	v_add_u32_e32 v2, 0x19000000, v0
	v_add_u32_e32 v4, 0x1afffe00, v0
	v_add_u32_e32 v6, 0x1cfffc00, v0
	s_lshl_b32 s2, s0, 8
	v_and_b32_e32 v8, 15, v76
	v_lshlrev_b32_e32 v8, 4, v8
	v_add_u32_e32 v8, s2, v8
	v_add_u32_e32 v8, 0x1efffa00, v8
	s_mov_b32 s15, 0
	s_mov_b32 s18, 0
.Lscan_ldsmall_pro:
	s_add_i32 s16, s15, 0x2000
	s_mov_b32 m0, s16
	s_mov_b32 exec_hi, 0
	s_add_i32 s15, s15, 0x2800
	global_load_lds_dwordx4 v2, s[90:91]
	global_load_lds_dwordx4 v4, s[90:91] offset:512
	global_load_lds_dwordx4 v6, s[90:91] offset:1024
	s_mov_b32 exec_lo, 0xffff
	s_cmp_eq_u32 s15, 0x25800
	global_load_lds_dwordx4 v8, s[90:91] offset:1536
	s_mov_b64 exec, -1
	s_cselect_b32 s15, 0, s15
	v_add_u32_e32 v2, 0x8000, v2
	v_add_u32_e32 v4, 0x8000, v4
	v_add_u32_e32 v6, 0x8000, v6
	v_add_u32_e32 v8, 0x1000, v8
	s_add_i32 s18, s18, 1
	s_cmp_lt_u32 s18, 12
	s_cbranch_scc1 .Lscan_ldsmall_pro
	s_waitcnt vmcnt(36)
	s_barrier
	s_mov_b32 s18, 0
	s_movk_i32 s17, 0x100

; #define SP_BAR() asm volatile("s_waitcnt lgkmcnt(0)\n\ts_barrier" ::: "memory")
; #define SP_WAIT() asm volatile("s_waitcnt vmcnt(36)" ::: "memory")
; __device__ __forceinline__ void rw_dma_issue(DmaPtrs& P, int lw, int lane, unsigned slot_lds) {
;     if (lw < 2) {
; #pragma unroll
;         for (int q = 0; q < 4; ++q) attn_body::glds16(P.p[q], (unsigned)__builtin_amdgcn_readfirstlane(slot_lds + P.off[q]));
;     } else {
;         if (lane < 32) {
; #pragma unroll
;             for (int q = 0; q < 3; ++q) attn_body::glds16(P.p[q], (unsigned)__builtin_amdgcn_readfirstlane(slot_lds + P.off[q])); }
;         if (lane < 16) attn_body::glds16(P.p[3], (unsigned)__builtin_amdgcn_readfirstlane(slot_lds + P.off[3]));
;     }
; #pragma unroll
;     for (int q = 0; q < 4; ++q) P.p[q] += (lw == 2 && q == 3) ? 16 * 256 : 16 * 2048;
; }
; __device__ __forceinline__ void p3_rwkv_state(Frame& F, const Args& a) {
;     ...
;         for (int n = 0; n < NC; n += 2) {
;             if (n + SP_D + 1 < NC) { rw_dma_issue(P, lw, lane, lds0 + (unsigned)((n + SP_D) % SP_R) * SP_SLOT); rw_dma_issue(P, lw, lane, lds0 + (unsigned)((n + SP_D + 1) % SP_R) * SP_SLOT); SP_WAIT(); }
;             else asm volatile("s_waitcnt vmcnt(0)" ::: "memory");
;             SP_BAR();
.Lscan_ldsmall_go:
	s_add_i32 s16, s15, 0x2000
	s_mov_b32 m0, s16
	s_mov_b32 exec_hi, 0
	s_add_i32 s15, s15, 0x2800
	global_load_lds_dwordx4 v2, s[90:91]
	global_load_lds_dwordx4 v4, s[90:91] offset:512
	global_load_lds_dwordx4 v6, s[90:91] offset:1024
	s_mov_b32 exec_lo, 0xffff
	s_cmp_eq_u32 s15, 0x25800
	global_load_lds_dwordx4 v8, s[90:91] offset:1536
	s_mov_b64 exec, -1
	s_cselect_b32 s15, 0, s15
	v_add_u32_e32 v2, 0x8000, v2
	v_add_u32_e32 v4, 0x8000, v4
	v_add_u32_e32 v6, 0x8000, v6
	v_add_u32_e32 v8, 0x1000, v8
	s_add_i32 s16, s15, 0x2000
	s_mov_b32 m0, s16
	s_mov_b32 exec_hi, 0
	s_add_i32 s15, s15, 0x2800
	global_load_lds_dwordx4 v2, s[90:91]
	global_load_lds_dwordx4 v4, s[90:91] offset:512
	global_load_lds_dwordx4 v6, s[90:91] offset:1024
	s_mov_b32 exec_lo, 0xffff
	s_cmp_eq_u32 s15, 0x25800
	global_load_lds_dwordx4 v8, s[90:91] offset:1536
	s_mov_b64 exec, -1
	s_cselect_b32 s15, 0, s15
	v_add_u32_e32 v2, 0x8000, v2
	v_add_u32_e32 v4, 0x8000, v4
	v_add_u32_e32 v6, 0x8000, v6
	v_add_u32_e32 v8, 0x1000, v8
	s_waitcnt vmcnt(36)
	s_branch .Lscan_ldsmall_bar
